# residual epilogues (out_proj, down_proj): non-temporal hint on the read-once f32 residual loads
# baseline (speedup 1.0000x reference)
.LBB0_1232:
	s_lshl_b32 s20, s44, 8
	v_mov_b32_e32 v2, v0
	s_lshl_b32 s18, s45, 8
	s_ashr_i32 s21, s20, 31
	s_add_i32 s11, s18, s37
	v_and_b32_e32 v220, 15, v2
	s_or_b64 s[22:23], s[20:21], s[54:55]
	s_lshl_b64 s[20:21], s[20:21], 2
	v_bfe_u32 v2, v2, 4, 2
	v_or_b32_e32 v202, s11, v220
	s_add_u32 s20, s40, s20
	v_lshl_or_b32 v200, v2, 3, s22
	v_cmp_eq_u32_e32 vcc, 0, v2
	s_addc_u32 s21, s41, s21
	v_lshlrev_b32_e32 v2, 5, v2
	v_ashrrev_i32_e32 v203, 31, v202
	v_lshl_add_u64 v[204:205], s[20:21], 0, v[2:3]
	v_lshlrev_b64 v[132:133], 13, v[202:203]
	v_lshl_add_u64 v[132:133], v[204:205], 0, v[132:133]
	global_load_dwordx4 v[222:225], v[132:133], off offset:16 nt
	global_load_dwordx4 v[226:229], v[132:133], off nt
	global_load_dwordx4 v[180:183], v[132:133], off offset:528 nt
	global_load_dwordx4 v[184:187], v[132:133], off offset:512 nt
	v_or_b32_e32 v210, 16, v202
	v_ashrrev_i32_e32 v211, 31, v210
	v_lshlrev_b64 v[132:133], 13, v[210:211]
	v_or_b32_e32 v208, 32, v202
	v_lshl_add_u64 v[132:133], v[204:205], 0, v[132:133]
	v_ashrrev_i32_e32 v209, 31, v208
	global_load_dwordx4 v[172:175], v[132:133], off offset:16 nt
	global_load_dwordx4 v[176:179], v[132:133], off nt
	global_load_dwordx4 v[164:167], v[132:133], off offset:528 nt
	global_load_dwordx4 v[168:171], v[132:133], off offset:512 nt
	v_lshlrev_b64 v[132:133], 13, v[208:209]
	v_or_b32_e32 v206, 48, v202
	v_lshl_add_u64 v[132:133], v[204:205], 0, v[132:133]
	v_ashrrev_i32_e32 v207, 31, v206
	global_load_dwordx4 v[156:159], v[132:133], off offset:16 nt
	global_load_dwordx4 v[160:163], v[132:133], off nt
	global_load_dwordx4 v[140:143], v[132:133], off offset:528 nt
	global_load_dwordx4 v[148:151], v[132:133], off offset:512 nt
	v_lshlrev_b64 v[132:133], 13, v[206:207]
	v_lshl_add_u64 v[136:137], v[204:205], 0, v[132:133]
	global_load_dwordx4 v[144:147], v[136:137], off offset:16 nt
	global_load_dwordx4 v[152:155], v[136:137], off nt
	global_load_dwordx4 v[132:135], v[136:137], off offset:528 nt
	s_nop 0
	global_load_dwordx4 v[136:139], v[136:137], off offset:512 nt
	v_mov_b32_e32 v201, s23
	v_lshlrev_b64 v[230:231], 11, v[202:203]
	v_lshl_add_u64 v[230:231], v[200:201], 0, v[230:231]
	s_waitcnt vmcnt(0)
	v_pk_add_f32 v[126:127], v[126:127], v[224:225]
	v_pk_add_f32 v[128:129], v[128:129], v[226:227]
	v_pk_add_f32 v[130:131], v[130:131], v[228:229]
	v_lshl_add_u64 v[226:227], v[230:231], 2, s[0:1]
	v_mul_f32_e32 v2, v129, v129
	v_pk_add_f32 v[124:125], v[124:125], v[222:223]
	global_store_dwordx4 v[226:227], v[128:131], off
	global_store_dwordx4 v[226:227], v[124:127], off offset:16
	v_cvt_pk_bf16_f32 v222, v128, v129
	v_fmac_f32_e32 v2, v128, v128
	v_mul_f32_e32 v128, v130, v130
	v_cvt_pk_bf16_f32 v224, v124, v125
	v_fmac_f32_e32 v128, v131, v131
	v_mul_f32_e32 v124, v124, v124
	v_add_f32_e32 v2, v2, v128
	v_fmac_f32_e32 v124, v125, v125
	v_lshlrev_b64 v[228:229], 1, v[230:231]
	v_add_f32_e32 v2, v124, v2
	v_mul_f32_e32 v124, v126, v126
	v_lshl_add_u64 v[230:231], s[6:7], 0, v[228:229]
	v_fmac_f32_e32 v124, v127, v127
	v_pk_add_f32 v[122:123], v[122:123], v[186:187]
	v_pk_add_f32 v[120:121], v[120:121], v[184:185]
	v_cvt_pk_bf16_f32 v223, v130, v131
	v_cvt_pk_bf16_f32 v225, v126, v127
	global_store_dwordx4 v[230:231], v[222:225], off
	v_add_f32_e32 v2, v124, v2
	v_pk_add_f32 v[118:119], v[118:119], v[182:183]
	v_pk_add_f32 v[116:117], v[116:117], v[180:181]
	global_store_dwordx4 v[226:227], v[120:123], off offset:512
	global_store_dwordx4 v[226:227], v[116:119], off offset:528
	v_cvt_pk_bf16_f32 v124, v120, v121
	v_cvt_pk_bf16_f32 v126, v116, v117
	v_or_b32_e32 v228, 0x100, v228
	v_mul_f32_e32 v121, v121, v121
	v_fmac_f32_e32 v121, v120, v120
	v_mul_f32_e32 v120, v122, v122
	v_fmac_f32_e32 v120, v123, v123
	v_mul_f32_e32 v116, v116, v116
	v_add_f32_e32 v120, v121, v120
	v_fmac_f32_e32 v116, v117, v117
	v_mul_f32_e32 v117, v118, v118
	v_add_f32_e32 v116, v116, v120
	v_fmac_f32_e32 v117, v119, v119
	v_add_f32_e32 v116, v117, v116
	v_lshl_add_u64 v[128:129], s[6:7], 0, v[228:229]
	v_add_f32_e32 v2, v2, v116
	v_mov_b32_e32 v116, v0
	v_cvt_pk_bf16_f32 v125, v122, v123
	v_cvt_pk_bf16_f32 v127, v118, v119
	global_store_dwordx4 v[128:129], v[124:127], off
	s_nop 0
	v_lshlrev_b32_e32 v116, 2, v116
	v_bitop3_b32 v116, v116, 64, v252 bitop3:0x6c
	ds_bpermute_b32 v116, v116, v2
	s_waitcnt lgkmcnt(0)
	v_add_f32_e32 v2, v2, v116
	v_mov_b32_e32 v116, v0
	s_nop 0
	v_lshlrev_b32_e32 v116, 2, v116
	v_bitop3_b32 v116, v116, s93, v252 bitop3:0x6c
	ds_bpermute_b32 v116, v116, v2
	s_and_saveexec_b64 s[20:21], vcc
	s_movk_i32 s47, 0xbf
	s_mov_b64 s[48:49], 0x4000
	s_cbranch_execz .LBB0_1234
	v_lshl_add_u32 v117, v220, 2, s42
	s_waitcnt lgkmcnt(0)
	v_add_f32_e32 v2, v2, v116
	ds_write_b32 v117, v2

.LBB0_1240:
	s_or_b64 exec, exec, s[20:21]
	v_add_u32_e32 v138, 0x80, v202
	v_ashrrev_i32_e32 v139, 31, v138
	s_waitcnt lgkmcnt(0)
	v_lshlrev_b64 v[68:69], 13, v[138:139]
	v_lshl_add_u64 v[68:69], v[204:205], 0, v[68:69]
	global_load_dwordx4 v[122:125], v[68:69], off offset:16 nt
	global_load_dwordx4 v[126:129], v[68:69], off nt
	global_load_dwordx4 v[130:133], v[68:69], off offset:528 nt
	global_load_dwordx4 v[134:137], v[68:69], off offset:512 nt
	v_add_u32_e32 v120, 0x90, v202
	v_ashrrev_i32_e32 v121, 31, v120
	v_lshlrev_b64 v[68:69], 13, v[120:121]
	v_add_u32_e32 v118, 0xa0, v202
	v_lshl_add_u64 v[68:69], v[204:205], 0, v[68:69]
	v_ashrrev_i32_e32 v119, 31, v118
	global_load_dwordx4 v[108:111], v[68:69], off offset:16 nt
	global_load_dwordx4 v[112:115], v[68:69], off nt
	global_load_dwordx4 v[100:103], v[68:69], off offset:528 nt
	global_load_dwordx4 v[104:107], v[68:69], off offset:512 nt
	v_lshlrev_b64 v[68:69], 13, v[118:119]
	v_add_u32_e32 v116, 0xb0, v202
	v_lshl_add_u64 v[68:69], v[204:205], 0, v[68:69]
	v_ashrrev_i32_e32 v117, 31, v116
	global_load_dwordx4 v[92:95], v[68:69], off offset:16 nt
	global_load_dwordx4 v[96:99], v[68:69], off nt
	global_load_dwordx4 v[76:79], v[68:69], off offset:528 nt
	global_load_dwordx4 v[84:87], v[68:69], off offset:512 nt
	v_lshlrev_b64 v[68:69], 13, v[116:117]
	v_lshl_add_u64 v[72:73], v[204:205], 0, v[68:69]
	global_load_dwordx4 v[80:83], v[72:73], off offset:16 nt
	global_load_dwordx4 v[88:91], v[72:73], off nt
	global_load_dwordx4 v[68:71], v[72:73], off offset:528 nt
	s_nop 0
	global_load_dwordx4 v[72:75], v[72:73], off offset:512 nt
	v_lshlrev_b64 v[138:139], 11, v[138:139]
	v_lshl_add_u64 v[138:139], v[138:139], 0, v[200:201]
	s_waitcnt vmcnt(15)
	v_pk_add_f32 v[62:63], v[62:63], v[124:125]
	s_waitcnt vmcnt(14)
	v_pk_add_f32 v[64:65], v[64:65], v[126:127]
	v_pk_add_f32 v[66:67], v[66:67], v[128:129]
	v_lshl_add_u64 v[126:127], v[138:139], 2, s[0:1]
	v_mul_f32_e32 v2, v65, v65
	v_pk_add_f32 v[60:61], v[60:61], v[122:123]
	global_store_dwordx4 v[126:127], v[64:67], off
	global_store_dwordx4 v[126:127], v[60:63], off offset:16
	v_cvt_pk_bf16_f32 v122, v64, v65
	v_fmac_f32_e32 v2, v64, v64
	v_mul_f32_e32 v64, v66, v66
	v_cvt_pk_bf16_f32 v124, v60, v61
	v_fmac_f32_e32 v64, v67, v67
	v_mul_f32_e32 v60, v60, v60
	v_add_f32_e32 v2, v2, v64
	v_fmac_f32_e32 v60, v61, v61
	v_lshlrev_b64 v[128:129], 1, v[138:139]
	v_add_f32_e32 v2, v60, v2
	v_mul_f32_e32 v60, v62, v62
	v_lshl_add_u64 v[138:139], s[6:7], 0, v[128:129]
	v_fmac_f32_e32 v60, v63, v63
	s_waitcnt vmcnt(14)
	v_pk_add_f32 v[58:59], v[58:59], v[136:137]
	v_pk_add_f32 v[56:57], v[56:57], v[134:135]
	v_cvt_pk_bf16_f32 v123, v66, v67
	v_cvt_pk_bf16_f32 v125, v62, v63
	global_store_dwordx4 v[138:139], v[122:125], off
	v_add_f32_e32 v2, v60, v2
	v_pk_add_f32 v[54:55], v[54:55], v[132:133]
	v_pk_add_f32 v[52:53], v[52:53], v[130:131]
	global_store_dwordx4 v[126:127], v[56:59], off offset:512
	global_store_dwordx4 v[126:127], v[52:55], off offset:528
	v_cvt_pk_bf16_f32 v60, v56, v57
	v_cvt_pk_bf16_f32 v62, v52, v53
	v_or_b32_e32 v128, 0x100, v128
	v_mul_f32_e32 v57, v57, v57
	v_fmac_f32_e32 v57, v56, v56
	v_mul_f32_e32 v56, v58, v58
	v_fmac_f32_e32 v56, v59, v59
	v_mul_f32_e32 v52, v52, v52
	v_add_f32_e32 v56, v57, v56
	v_fmac_f32_e32 v52, v53, v53
	v_mul_f32_e32 v53, v54, v54
	v_add_f32_e32 v52, v52, v56
	v_fmac_f32_e32 v53, v55, v55
	v_add_f32_e32 v52, v53, v52
	v_lshl_add_u64 v[64:65], s[6:7], 0, v[128:129]
	v_add_f32_e32 v2, v2, v52
	v_mov_b32_e32 v52, v0
	v_cvt_pk_bf16_f32 v61, v58, v59
	v_cvt_pk_bf16_f32 v63, v54, v55
	global_store_dwordx4 v[64:65], v[60:63], off
	s_nop 0
	v_lshlrev_b32_e32 v52, 2, v52
	v_bitop3_b32 v52, v52, 64, v252 bitop3:0x6c
	ds_bpermute_b32 v52, v52, v2
	s_waitcnt lgkmcnt(0)
	v_add_f32_e32 v2, v2, v52
	v_mov_b32_e32 v52, v0
	s_nop 0
	v_lshlrev_b32_e32 v52, 2, v52
	v_bitop3_b32 v52, v52, s93, v252 bitop3:0x6c
	ds_bpermute_b32 v52, v52, v2
	s_and_saveexec_b64 s[20:21], vcc
	s_cbranch_execz .LBB0_1242
	v_lshl_add_u32 v53, v220, 2, s42
	s_waitcnt lgkmcnt(0)
	v_add_f32_e32 v2, v2, v52
	ds_write_b32 v53, v2 offset:256

.LBB0_1507:
	v_mov_b32_e32 v2, v0
	s_lshl_b32 s22, s49, 8
	s_add_i32 s4, s22, s37
	v_and_b32_e32 v220, 15, v2
	v_or_b32_e32 v202, s4, v220
	s_lshl_b32 s4, s46, 8
	s_ashr_i32 s5, s4, 31
	s_or_b64 s[24:25], s[4:5], s[54:55]
	s_lshl_b64 s[4:5], s[4:5], 2
	v_bfe_u32 v221, v2, 4, 2
	s_add_u32 s4, s42, s4
	s_addc_u32 s5, s43, s5
	v_lshlrev_b32_e32 v2, 5, v221
	v_ashrrev_i32_e32 v203, 31, v202
	v_lshl_add_u64 v[204:205], s[4:5], 0, v[2:3]
	v_lshlrev_b64 v[124:125], 13, v[202:203]
	v_or_b32_e32 v210, 16, v202
	v_lshl_add_u64 v[124:125], v[204:205], 0, v[124:125]
	v_ashrrev_i32_e32 v211, 31, v210
	global_load_dwordx4 v[224:227], v[124:125], off offset:16 nt
	global_load_dwordx4 v[228:231], v[124:125], off nt
	global_load_dwordx4 v[180:183], v[124:125], off offset:528 nt
	global_load_dwordx4 v[184:187], v[124:125], off offset:512 nt
	v_lshlrev_b64 v[124:125], 13, v[210:211]
	v_or_b32_e32 v208, 32, v202
	v_lshl_add_u64 v[124:125], v[204:205], 0, v[124:125]
	v_ashrrev_i32_e32 v209, 31, v208
	global_load_dwordx4 v[172:175], v[124:125], off offset:16 nt
	global_load_dwordx4 v[176:179], v[124:125], off nt
	global_load_dwordx4 v[164:167], v[124:125], off offset:528 nt
	global_load_dwordx4 v[168:171], v[124:125], off offset:512 nt
	v_lshlrev_b64 v[124:125], 13, v[208:209]
	v_or_b32_e32 v206, 48, v202
	v_lshl_add_u64 v[124:125], v[204:205], 0, v[124:125]
	v_ashrrev_i32_e32 v207, 31, v206
	global_load_dwordx4 v[156:159], v[124:125], off offset:16 nt
	global_load_dwordx4 v[160:163], v[124:125], off nt
	global_load_dwordx4 v[148:151], v[124:125], off offset:528 nt
	global_load_dwordx4 v[152:155], v[124:125], off offset:512 nt
	v_lshlrev_b64 v[124:125], 13, v[206:207]
	v_lshl_add_u64 v[128:129], v[204:205], 0, v[124:125]
	global_load_dwordx4 v[132:135], v[128:129], off offset:16 nt
	global_load_dwordx4 v[136:139], v[128:129], off nt
	global_load_dwordx4 v[124:127], v[128:129], off offset:528 nt
	s_nop 0
	global_load_dwordx4 v[128:131], v[128:129], off offset:512 nt
	v_lshl_or_b32 v200, v221, 3, s24
	v_mov_b32_e32 v201, s25
	v_lshlrev_b64 v[222:223], 11, v[202:203]
	v_lshl_add_u64 v[222:223], v[200:201], 0, v[222:223]
	v_cndmask_b32_e64 v2, 0, 1, s[12:13]
	s_mov_b64 s[24:25], -1
	v_cmp_ne_u32_e64 s[4:5], 1, v2
	s_andn2_b64 vcc, exec, s[12:13]
	s_waitcnt vmcnt(0)
	v_pk_add_f32 v[142:143], v[142:143], v[226:227]
	v_pk_add_f32 v[146:147], v[146:147], v[230:231]
	v_pk_add_f32 v[144:145], v[144:145], v[228:229]
	v_pk_add_f32 v[140:141], v[140:141], v[224:225]
	v_lshl_add_u64 v[224:225], v[222:223], 2, s[2:3]
	global_store_dwordx4 v[224:225], v[144:147], off
	global_store_dwordx4 v[224:225], v[140:143], off offset:16
	s_cbranch_vccnz .LBB0_1509
	s_mov_b64 s[24:25], 0

.LBB0_1547:
	s_or_b64 exec, exec, s[26:27]
	v_add_u32_e32 v130, 0x80, v202
	v_ashrrev_i32_e32 v131, 31, v130
	s_waitcnt lgkmcnt(0)
	v_lshlrev_b64 v[68:69], 13, v[130:131]
	v_add_u32_e32 v128, 0x90, v202
	v_lshl_add_u64 v[68:69], v[204:205], 0, v[68:69]
	v_ashrrev_i32_e32 v129, 31, v128
	global_load_dwordx4 v[132:135], v[68:69], off offset:16 nt
	global_load_dwordx4 v[136:139], v[68:69], off nt
	global_load_dwordx4 v[116:119], v[68:69], off offset:528 nt
	global_load_dwordx4 v[120:123], v[68:69], off offset:512 nt
	v_lshlrev_b64 v[68:69], 13, v[128:129]
	v_add_u32_e32 v126, 0xa0, v202
	v_lshl_add_u64 v[68:69], v[204:205], 0, v[68:69]
	v_ashrrev_i32_e32 v127, 31, v126
	global_load_dwordx4 v[108:111], v[68:69], off offset:16 nt
	global_load_dwordx4 v[112:115], v[68:69], off nt
	global_load_dwordx4 v[100:103], v[68:69], off offset:528 nt
	global_load_dwordx4 v[104:107], v[68:69], off offset:512 nt
	v_lshlrev_b64 v[68:69], 13, v[126:127]
	v_add_u32_e32 v124, 0xb0, v202
	v_lshl_add_u64 v[68:69], v[204:205], 0, v[68:69]
	v_ashrrev_i32_e32 v125, 31, v124
	global_load_dwordx4 v[92:95], v[68:69], off offset:16 nt
	global_load_dwordx4 v[96:99], v[68:69], off nt
	global_load_dwordx4 v[84:87], v[68:69], off offset:528 nt
	global_load_dwordx4 v[88:91], v[68:69], off offset:512 nt
	v_lshlrev_b64 v[68:69], 13, v[124:125]
	v_lshl_add_u64 v[72:73], v[204:205], 0, v[68:69]
	global_load_dwordx4 v[76:79], v[72:73], off offset:16 nt
	global_load_dwordx4 v[80:83], v[72:73], off nt
	global_load_dwordx4 v[68:71], v[72:73], off offset:528 nt
	s_nop 0
	global_load_dwordx4 v[72:75], v[72:73], off offset:512 nt
	v_lshlrev_b64 v[130:131], 11, v[130:131]
	v_lshl_add_u64 v[130:131], v[130:131], 0, v[200:201]
	s_mov_b64 s[26:27], -1
	s_and_b64 vcc, exec, s[4:5]
	s_waitcnt vmcnt(15)
	v_pk_add_f32 v[62:63], v[62:63], v[134:135]
	s_waitcnt vmcnt(14)
	v_pk_add_f32 v[66:67], v[66:67], v[138:139]
	v_pk_add_f32 v[64:65], v[64:65], v[136:137]
	v_pk_add_f32 v[60:61], v[60:61], v[132:133]
	v_lshl_add_u64 v[132:133], v[130:131], 2, s[2:3]
	global_store_dwordx4 v[132:133], v[64:67], off
	global_store_dwordx4 v[132:133], v[60:63], off offset:16
	s_cbranch_vccnz .LBB0_1549
	s_mov_b64 s[26:27], 0
